# plus: NSA branch stage-out (LDS read-modify-write of the bf16 output stage) de-serialised into batches of 8 reads per wait instead of 64 dependent round trips
# speedup vs baseline: 1.0044x; 1.0011x over previous
; DI unsigned short f2bf1(float f) { return (unsigned short)(cvtpk(f, 0.f) & 0xffffu); }
; #define LDS_WAIT() asm volatile("s_waitcnt lgkmcnt(0)" ::: "memory")
; DI int crow(int r, int hi) { return (r & 3) + 8 * (r >> 2) + 4 * hi; }
; DI void nsa_stage_out(att::Core<128>& c, bf16_t* stg, float* ws, float fac, bool first, int r32, int hi) {
;     if (hi == 0) ws[r32] = fac;
;     LDS_WAIT();
; #pragma unroll
;     for (int r = 0; r < 16; ++r) { const int orow = att::crow(r, hi); const float f = ws[orow];
; #pragma unroll
;         for (int d0 = 0; d0 < 4; ++d0) { bf16_t* p = stg + orow * 136 + d0 * 32 + r32; float v = c.o[d0][r] * f; if (!first) v += bf2f(*p); *p = f2bf1(v); } }
;     LDS_WAIT();
; }
.LBB0_809:
	s_or_b64 exec, exec, s[2:3]
	s_waitcnt lgkmcnt(0)
	ds_read_b32 v86, v182
	ds_read_b32 v87, v182 offset:4
	ds_read_u16 v203, v199
	ds_read_u16 v204, v199 offset:64
	ds_read_u16 v205, v199 offset:128
	ds_read_u16 v206, v199 offset:192
	ds_read_u16 v207, v200
	ds_read_u16 v208, v200 offset:64
	ds_read_u16 v209, v200 offset:128
	ds_read_u16 v210, v200 offset:192
	s_waitcnt lgkmcnt(0)
	v_lshlrev_b32_e32 v203, 16, v203
	v_lshlrev_b32_e32 v204, 16, v204
	v_lshlrev_b32_e32 v205, 16, v205
	v_lshlrev_b32_e32 v206, 16, v206
	v_lshlrev_b32_e32 v207, 16, v207
	v_lshlrev_b32_e32 v208, 16, v208
	v_lshlrev_b32_e32 v209, 16, v209
	v_lshlrev_b32_e32 v210, 16, v210
	v_fmac_f32_e32 v203, v50, v86
	v_fmac_f32_e32 v204, v34, v86
	v_fmac_f32_e32 v205, v18, v86
	v_fmac_f32_e32 v206, v2, v86
	v_fmac_f32_e32 v207, v51, v87
	v_fmac_f32_e32 v208, v35, v87
	v_fmac_f32_e32 v209, v19, v87
	v_fmac_f32_e32 v210, v3, v87
	v_cvt_pk_bf16_f32 v203, v203, v1
	v_cvt_pk_bf16_f32 v204, v204, v1
	v_cvt_pk_bf16_f32 v205, v205, v1
	v_cvt_pk_bf16_f32 v206, v206, v1
	v_cvt_pk_bf16_f32 v207, v207, v1
	v_cvt_pk_bf16_f32 v208, v208, v1
	v_cvt_pk_bf16_f32 v209, v209, v1
	v_cvt_pk_bf16_f32 v210, v210, v1
	ds_write_b16 v199, v203
	ds_write_b16 v199, v204 offset:64
	ds_write_b16 v199, v205 offset:128
	ds_write_b16 v199, v206 offset:192
	ds_write_b16 v200, v207
	ds_write_b16 v200, v208 offset:64
	ds_write_b16 v200, v209 offset:128
	ds_write_b16 v200, v210 offset:192
	s_waitcnt lgkmcnt(5)
	ds_read_b32 v86, v182 offset:8
	ds_read_b32 v87, v182 offset:12
	ds_read_u16 v203, v200 offset:272
	ds_read_u16 v204, v200 offset:336
	ds_read_u16 v205, v200 offset:400
	ds_read_u16 v206, v200 offset:464
	ds_read_u16 v207, v200 offset:544
	ds_read_u16 v208, v200 offset:608
	ds_read_u16 v209, v200 offset:672
	ds_read_u16 v210, v200 offset:736
	s_waitcnt lgkmcnt(0)
	v_lshlrev_b32_e32 v203, 16, v203
	v_lshlrev_b32_e32 v204, 16, v204
	v_lshlrev_b32_e32 v205, 16, v205
	v_lshlrev_b32_e32 v206, 16, v206
	v_lshlrev_b32_e32 v207, 16, v207
	v_lshlrev_b32_e32 v208, 16, v208
	v_lshlrev_b32_e32 v209, 16, v209
	v_lshlrev_b32_e32 v210, 16, v210
	v_fmac_f32_e32 v203, v52, v86
	v_fmac_f32_e32 v204, v36, v86
	v_fmac_f32_e32 v205, v20, v86
	v_fmac_f32_e32 v206, v4, v86
	v_fmac_f32_e32 v207, v53, v87
	v_fmac_f32_e32 v208, v37, v87
	v_fmac_f32_e32 v209, v21, v87
	v_fmac_f32_e32 v210, v5, v87
	v_cvt_pk_bf16_f32 v203, v203, v1
	v_cvt_pk_bf16_f32 v204, v204, v1
	v_cvt_pk_bf16_f32 v205, v205, v1
	v_cvt_pk_bf16_f32 v206, v206, v1
	v_cvt_pk_bf16_f32 v207, v207, v1
	v_cvt_pk_bf16_f32 v208, v208, v1
	v_cvt_pk_bf16_f32 v209, v209, v1
	v_cvt_pk_bf16_f32 v210, v210, v1
	ds_write_b16 v200, v203 offset:272
	ds_write_b16 v200, v204 offset:336
	ds_write_b16 v200, v205 offset:400
	ds_write_b16 v200, v206 offset:464
	ds_write_b16 v200, v207 offset:544
	ds_write_b16 v200, v208 offset:608
	ds_write_b16 v200, v209 offset:672
	ds_write_b16 v200, v210 offset:736
	s_waitcnt lgkmcnt(5)
	ds_read_b32 v86, v182 offset:32
	ds_read_b32 v87, v182 offset:36
	ds_read_u16 v203, v200 offset:1904
	ds_read_u16 v204, v200 offset:1968
	ds_read_u16 v205, v200 offset:2032
	ds_read_u16 v206, v200 offset:2096
	ds_read_u16 v207, v200 offset:2176
	ds_read_u16 v208, v200 offset:2240
	ds_read_u16 v209, v200 offset:2304
	ds_read_u16 v210, v200 offset:2368
	s_waitcnt lgkmcnt(0)
	v_lshlrev_b32_e32 v203, 16, v203
	v_lshlrev_b32_e32 v204, 16, v204
	v_lshlrev_b32_e32 v205, 16, v205
	v_lshlrev_b32_e32 v206, 16, v206
	v_lshlrev_b32_e32 v207, 16, v207
	v_lshlrev_b32_e32 v208, 16, v208
	v_lshlrev_b32_e32 v209, 16, v209
	v_lshlrev_b32_e32 v210, 16, v210
	v_fmac_f32_e32 v203, v54, v86
	v_fmac_f32_e32 v204, v38, v86
	v_fmac_f32_e32 v205, v22, v86
	v_fmac_f32_e32 v206, v6, v86
	v_fmac_f32_e32 v207, v55, v87
	v_fmac_f32_e32 v208, v39, v87
	v_fmac_f32_e32 v209, v23, v87
	v_fmac_f32_e32 v210, v7, v87
	v_cvt_pk_bf16_f32 v203, v203, v1
	v_cvt_pk_bf16_f32 v204, v204, v1
	v_cvt_pk_bf16_f32 v205, v205, v1
	v_cvt_pk_bf16_f32 v206, v206, v1
	v_cvt_pk_bf16_f32 v207, v207, v1
	v_cvt_pk_bf16_f32 v208, v208, v1
	v_cvt_pk_bf16_f32 v209, v209, v1
	v_cvt_pk_bf16_f32 v210, v210, v1
	ds_write_b16 v200, v203 offset:1904
	ds_write_b16 v200, v204 offset:1968
	ds_write_b16 v200, v205 offset:2032
	ds_write_b16 v200, v206 offset:2096
	ds_write_b16 v200, v207 offset:2176
	ds_write_b16 v200, v208 offset:2240
	ds_write_b16 v200, v209 offset:2304
	ds_write_b16 v200, v210 offset:2368
	s_waitcnt lgkmcnt(5)
	ds_read_b32 v86, v182 offset:40
	ds_read_b32 v87, v182 offset:44
	ds_read_u16 v203, v200 offset:2448
	ds_read_u16 v204, v201 offset:64
	ds_read_u16 v205, v201 offset:128
	ds_read_u16 v206, v201 offset:192
	ds_read_u16 v207, v201 offset:272
	ds_read_u16 v208, v201 offset:336
	ds_read_u16 v209, v201 offset:400
	ds_read_u16 v210, v201 offset:464
	s_waitcnt lgkmcnt(0)
	v_lshlrev_b32_e32 v203, 16, v203
	v_lshlrev_b32_e32 v204, 16, v204
	v_lshlrev_b32_e32 v205, 16, v205
	v_lshlrev_b32_e32 v206, 16, v206
	v_lshlrev_b32_e32 v207, 16, v207
	v_lshlrev_b32_e32 v208, 16, v208
	v_lshlrev_b32_e32 v209, 16, v209
	v_lshlrev_b32_e32 v210, 16, v210
	v_fmac_f32_e32 v203, v56, v86
	v_fmac_f32_e32 v204, v40, v86
	v_fmac_f32_e32 v205, v24, v86
	v_fmac_f32_e32 v206, v8, v86
	v_fmac_f32_e32 v207, v57, v87
	v_fmac_f32_e32 v208, v41, v87
	v_fmac_f32_e32 v209, v25, v87
	v_fmac_f32_e32 v210, v9, v87
	v_cvt_pk_bf16_f32 v203, v203, v1
	v_cvt_pk_bf16_f32 v204, v204, v1
	v_cvt_pk_bf16_f32 v205, v205, v1
	v_cvt_pk_bf16_f32 v206, v206, v1
	v_cvt_pk_bf16_f32 v207, v207, v1
	v_cvt_pk_bf16_f32 v208, v208, v1
	v_cvt_pk_bf16_f32 v209, v209, v1
	v_cvt_pk_bf16_f32 v210, v210, v1
	ds_write_b16 v200, v203 offset:2448
	ds_write_b16 v201, v204 offset:64
	ds_write_b16 v201, v205 offset:128
	ds_write_b16 v201, v206 offset:192
	ds_write_b16 v201, v207 offset:272
	ds_write_b16 v201, v208 offset:336
	ds_write_b16 v201, v209 offset:400
	ds_write_b16 v201, v210 offset:464
	s_waitcnt lgkmcnt(5)
; DI unsigned short f2bf1(float f) { return (unsigned short)(cvtpk(f, 0.f) & 0xffffu); }
; #define LDS_WAIT() asm volatile("s_waitcnt lgkmcnt(0)" ::: "memory")
; DI int crow(int r, int hi) { return (r & 3) + 8 * (r >> 2) + 4 * hi; }
; DI void nsa_stage_out(att::Core<128>& c, bf16_t* stg, float* ws, float fac, bool first, int r32, int hi) {
;     if (hi == 0) ws[r32] = fac;
;     LDS_WAIT();
; #pragma unroll
;     for (int r = 0; r < 16; ++r) { const int orow = att::crow(r, hi); const float f = ws[orow];
; #pragma unroll
;         for (int d0 = 0; d0 < 4; ++d0) { bf16_t* p = stg + orow * 136 + d0 * 32 + r32; float v = c.o[d0][r] * f; if (!first) v += bf2f(*p); *p = f2bf1(v); } }
;     LDS_WAIT();
; }
	ds_read_b32 v86, v182 offset:64
	ds_read_b32 v87, v182 offset:68
	ds_read_u16 v203, v201 offset:1632
	ds_read_u16 v204, v201 offset:1696
	ds_read_u16 v205, v201 offset:1760
	ds_read_u16 v206, v201 offset:1824
	ds_read_u16 v207, v201 offset:1904
	ds_read_u16 v208, v201 offset:1968
	ds_read_u16 v209, v201 offset:2032
	ds_read_u16 v210, v201 offset:2096
	s_waitcnt lgkmcnt(0)
	v_lshlrev_b32_e32 v203, 16, v203
	v_lshlrev_b32_e32 v204, 16, v204
	v_lshlrev_b32_e32 v205, 16, v205
	v_lshlrev_b32_e32 v206, 16, v206
	v_lshlrev_b32_e32 v207, 16, v207
	v_lshlrev_b32_e32 v208, 16, v208
	v_lshlrev_b32_e32 v209, 16, v209
	v_lshlrev_b32_e32 v210, 16, v210
	v_fmac_f32_e32 v203, v58, v86
	v_fmac_f32_e32 v204, v42, v86
	v_fmac_f32_e32 v205, v26, v86
	v_fmac_f32_e32 v206, v10, v86
	v_fmac_f32_e32 v207, v59, v87
	v_fmac_f32_e32 v208, v43, v87
	v_fmac_f32_e32 v209, v27, v87
	v_fmac_f32_e32 v210, v11, v87
	v_cvt_pk_bf16_f32 v203, v203, v1
	v_cvt_pk_bf16_f32 v204, v204, v1
	v_cvt_pk_bf16_f32 v205, v205, v1
	v_cvt_pk_bf16_f32 v206, v206, v1
	v_cvt_pk_bf16_f32 v207, v207, v1
	v_cvt_pk_bf16_f32 v208, v208, v1
	v_cvt_pk_bf16_f32 v209, v209, v1
	v_cvt_pk_bf16_f32 v210, v210, v1
	ds_write_b16 v201, v203 offset:1632
	ds_write_b16 v201, v204 offset:1696
	ds_write_b16 v201, v205 offset:1760
	ds_write_b16 v201, v206 offset:1824
	ds_write_b16 v201, v207 offset:1904
	ds_write_b16 v201, v208 offset:1968
	ds_write_b16 v201, v209 offset:2032
	ds_write_b16 v201, v210 offset:2096
	s_waitcnt lgkmcnt(5)
	ds_read_b32 v86, v182 offset:72
	ds_read_b32 v87, v182 offset:76
	ds_read_u16 v203, v201 offset:2176
	ds_read_u16 v204, v201 offset:2240
	ds_read_u16 v205, v201 offset:2304
	ds_read_u16 v206, v201 offset:2368
	ds_read_u16 v207, v201 offset:2448
	ds_read_u16 v208, v202 offset:64
	ds_read_u16 v209, v202 offset:128
	ds_read_u16 v210, v202 offset:192
	s_waitcnt lgkmcnt(0)
	v_lshlrev_b32_e32 v203, 16, v203
	v_lshlrev_b32_e32 v204, 16, v204
	v_lshlrev_b32_e32 v205, 16, v205
	v_lshlrev_b32_e32 v206, 16, v206
	v_lshlrev_b32_e32 v207, 16, v207
	v_lshlrev_b32_e32 v208, 16, v208
	v_lshlrev_b32_e32 v209, 16, v209
	v_lshlrev_b32_e32 v210, 16, v210
	v_fmac_f32_e32 v203, v60, v86
	v_fmac_f32_e32 v204, v44, v86
	v_fmac_f32_e32 v205, v28, v86
	v_fmac_f32_e32 v206, v12, v86
	v_fmac_f32_e32 v207, v61, v87
	v_fmac_f32_e32 v208, v45, v87
	v_fmac_f32_e32 v209, v29, v87
	v_fmac_f32_e32 v210, v13, v87
	v_cvt_pk_bf16_f32 v203, v203, v1
	v_cvt_pk_bf16_f32 v204, v204, v1
	v_cvt_pk_bf16_f32 v205, v205, v1
	v_cvt_pk_bf16_f32 v206, v206, v1
	v_cvt_pk_bf16_f32 v207, v207, v1
	v_cvt_pk_bf16_f32 v208, v208, v1
	v_cvt_pk_bf16_f32 v209, v209, v1
	v_cvt_pk_bf16_f32 v210, v210, v1
	ds_write_b16 v201, v203 offset:2176
	ds_write_b16 v201, v204 offset:2240
	ds_write_b16 v201, v205 offset:2304
	ds_write_b16 v201, v206 offset:2368
	ds_write_b16 v201, v207 offset:2448
	ds_write_b16 v202, v208 offset:64
	ds_write_b16 v202, v209 offset:128
	ds_write_b16 v202, v210 offset:192
	s_waitcnt lgkmcnt(5)
	ds_read_b32 v86, v182 offset:96
	ds_read_b32 v87, v182 offset:100
	ds_read_u16 v203, v202 offset:1360
	ds_read_u16 v204, v202 offset:1424
	ds_read_u16 v205, v202 offset:1488
	ds_read_u16 v206, v202 offset:1552
	ds_read_u16 v207, v202 offset:1632
	ds_read_u16 v208, v202 offset:1696
	ds_read_u16 v209, v202 offset:1760
	ds_read_u16 v210, v202 offset:1824
	s_waitcnt lgkmcnt(0)
	v_lshlrev_b32_e32 v203, 16, v203
	v_lshlrev_b32_e32 v204, 16, v204
	v_lshlrev_b32_e32 v205, 16, v205
	v_lshlrev_b32_e32 v206, 16, v206
	v_lshlrev_b32_e32 v207, 16, v207
	v_lshlrev_b32_e32 v208, 16, v208
	v_lshlrev_b32_e32 v209, 16, v209
	v_lshlrev_b32_e32 v210, 16, v210
	v_fmac_f32_e32 v203, v62, v86
	v_fmac_f32_e32 v204, v46, v86
	v_fmac_f32_e32 v205, v30, v86
	v_fmac_f32_e32 v206, v14, v86
	v_fmac_f32_e32 v207, v63, v87
	v_fmac_f32_e32 v208, v47, v87
	v_fmac_f32_e32 v209, v31, v87
	v_fmac_f32_e32 v210, v15, v87
	v_cvt_pk_bf16_f32 v203, v203, v1
	v_cvt_pk_bf16_f32 v204, v204, v1
	v_cvt_pk_bf16_f32 v205, v205, v1
	v_cvt_pk_bf16_f32 v206, v206, v1
	v_cvt_pk_bf16_f32 v207, v207, v1
	v_cvt_pk_bf16_f32 v208, v208, v1
	v_cvt_pk_bf16_f32 v209, v209, v1
	v_cvt_pk_bf16_f32 v210, v210, v1
	ds_write_b16 v202, v203 offset:1360
	ds_write_b16 v202, v204 offset:1424
	ds_write_b16 v202, v205 offset:1488
	ds_write_b16 v202, v206 offset:1552
	ds_write_b16 v202, v207 offset:1632
	ds_write_b16 v202, v208 offset:1696
	ds_write_b16 v202, v209 offset:1760
	ds_write_b16 v202, v210 offset:1824
	s_waitcnt lgkmcnt(5)
	ds_read_b32 v86, v182 offset:104
	ds_read_b32 v87, v182 offset:108
	ds_read_u16 v203, v202 offset:1904
	ds_read_u16 v204, v202 offset:1968
	ds_read_u16 v205, v202 offset:2032
	ds_read_u16 v206, v202 offset:2096
	ds_read_u16 v207, v202 offset:2176
	ds_read_u16 v208, v202 offset:2240
	ds_read_u16 v209, v202 offset:2304
	ds_read_u16 v210, v202 offset:2368
	s_waitcnt lgkmcnt(0)
; #define GAS __attribute__((address_space(1)))
; DI unsigned short f2bf1(float f) { return (unsigned short)(cvtpk(f, 0.f) & 0xffffu); }
; #define LDS_WAIT() asm volatile("s_waitcnt lgkmcnt(0)" ::: "memory")
; DI int crow(int r, int hi) { return (r & 3) + 8 * (r >> 2) + 4 * hi; }
; DI unsigned char* arg_ws() { return (unsigned char*)karg_u64<200>(); }
; DI void nsa_stage_out(att::Core<128>& c, bf16_t* stg, float* ws, float fac, bool first, int r32, int hi) {
;     if (hi == 0) ws[r32] = fac;
;     LDS_WAIT();
; #pragma unroll
;     for (int r = 0; r < 16; ++r) { const int orow = att::crow(r, hi); const float f = ws[orow];
; #pragma unroll
;         for (int d0 = 0; d0 < 4; ++d0) { bf16_t* p = stg + orow * 136 + d0 * 32 + r32; float v = c.o[d0][r] * f; if (!first) v += bf2f(*p); *p = f2bf1(v); } }
;     LDS_WAIT();
; }
; DI void nsa_attention(int L2, char* lds, int vcu, int G, int tid, int wave, int lane) {
;     ...
; #pragma unroll
;         for (int i = 0; i < 8; ++i) { const int row = i * 4 + (lane >> 4), ch = lane & 15; const u32x4 v = *(const u32x4*)(stg + row * 136 + ch * 8);
;             *(GAS u32x4*)((bf16_t*)(arg_ws() + WS_OB) + (size_t)(b * T + t0 + 8 * wave + (row >> 2)) * DM + (4 * g + (row & 3)) * 128 + ch * 8) = v; }
;         LDS_WAIT();
;         __syncthreads();
	v_lshlrev_b32_e32 v203, 16, v203
	v_lshlrev_b32_e32 v204, 16, v204
	v_lshlrev_b32_e32 v205, 16, v205
	v_lshlrev_b32_e32 v206, 16, v206
	v_lshlrev_b32_e32 v207, 16, v207
	v_lshlrev_b32_e32 v208, 16, v208
	v_lshlrev_b32_e32 v209, 16, v209
	v_lshlrev_b32_e32 v210, 16, v210
	v_fmac_f32_e32 v203, v64, v86
	v_fmac_f32_e32 v204, v48, v86
	v_fmac_f32_e32 v205, v32, v86
	v_fmac_f32_e32 v206, v16, v86
	v_fmac_f32_e32 v207, v65, v87
	v_fmac_f32_e32 v208, v49, v87
	v_fmac_f32_e32 v209, v33, v87
	v_fmac_f32_e32 v210, v17, v87
	v_cvt_pk_bf16_f32 v203, v203, v1
	v_cvt_pk_bf16_f32 v204, v204, v1
	v_cvt_pk_bf16_f32 v205, v205, v1
	v_cvt_pk_bf16_f32 v206, v206, v1
	v_cvt_pk_bf16_f32 v207, v207, v1
	v_cvt_pk_bf16_f32 v208, v208, v1
	v_cvt_pk_bf16_f32 v209, v209, v1
	v_cvt_pk_bf16_f32 v210, v210, v1
	ds_write_b16 v202, v203 offset:1904
	ds_write_b16 v202, v204 offset:1968
	ds_write_b16 v202, v205 offset:2032
	ds_write_b16 v202, v206 offset:2096
	ds_write_b16 v202, v207 offset:2176
	ds_write_b16 v202, v208 offset:2240
	ds_write_b16 v202, v209 offset:2304
	ds_write_b16 v202, v210 offset:2368
	s_add_i32 s2, s86, s71
	s_add_i32 s2, s2, s79
	s_ashr_i32 s3, s2, 31
	s_lshl_b64 s[4:5], s[2:3], 12
	v_mov_b32_e32 v169, v1
	v_or_b32_e32 v4, s80, v242
	v_lshlrev_b32_e32 v0, 8, v4
	s_waitcnt lgkmcnt(0)
	ds_read_b128 v[2:5], v198
	s_load_dwordx2 s[12:13], s[0:1], 0xc8
	s_waitcnt lgkmcnt(0)
	s_add_u32 s4, s12, s4
	s_addc_u32 s5, s13, s5
	v_lshl_add_u64 v[10:11], s[4:5], 0, v[0:1]
	s_or_b32 s12, s2, 1
	v_lshl_add_u64 v[10:11], v[10:11], 0, v[168:169]
	s_ashr_i32 s13, s12, 31
	v_add_co_u32_e32 v10, vcc, s75, v10
	s_lshl_b64 s[4:5], s[12:13], 12
	s_nop 0
	v_addc_co_u32_e32 v11, vcc, 0, v11, vcc
	ds_read_b128 v[6:9], v198 offset:1088
	s_waitcnt lgkmcnt(1)
	global_store_dwordx4 v[10:11], v[2:5], off
	s_load_dwordx2 s[12:13], s[0:1], 0xc8
	s_waitcnt lgkmcnt(0)
	s_add_u32 s4, s12, s4
	s_addc_u32 s5, s13, s5
	v_lshl_add_u64 v[10:11], s[4:5], 0, v[0:1]
	s_or_b32 s12, s2, 2
	v_lshl_add_u64 v[10:11], v[10:11], 0, v[168:169]
	s_ashr_i32 s13, s12, 31
	v_add_co_u32_e32 v10, vcc, s75, v10
	s_lshl_b64 s[4:5], s[12:13], 12
	s_nop 0
	v_addc_co_u32_e32 v11, vcc, 0, v11, vcc
	ds_read_b128 v[2:5], v198 offset:2176
	s_waitcnt lgkmcnt(1)
	global_store_dwordx4 v[10:11], v[6:9], off
	s_load_dwordx2 s[12:13], s[0:1], 0xc8
	s_waitcnt lgkmcnt(0)
	s_add_u32 s4, s12, s4
	s_addc_u32 s5, s13, s5
	v_lshl_add_u64 v[10:11], s[4:5], 0, v[0:1]
	s_or_b32 s12, s2, 3
	v_lshl_add_u64 v[10:11], v[10:11], 0, v[168:169]
	s_ashr_i32 s13, s12, 31
	v_add_co_u32_e32 v10, vcc, s75, v10
	s_lshl_b64 s[4:5], s[12:13], 12
	s_nop 0
	v_addc_co_u32_e32 v11, vcc, 0, v11, vcc
	ds_read_b128 v[6:9], v198 offset:3264
	s_waitcnt lgkmcnt(1)
	global_store_dwordx4 v[10:11], v[2:5], off
	s_load_dwordx2 s[12:13], s[0:1], 0xc8
	s_waitcnt lgkmcnt(0)
	s_add_u32 s4, s12, s4
	s_addc_u32 s5, s13, s5
	v_lshl_add_u64 v[10:11], s[4:5], 0, v[0:1]
	s_or_b32 s12, s2, 4
	v_lshl_add_u64 v[10:11], v[10:11], 0, v[168:169]
	s_ashr_i32 s13, s12, 31
	v_add_co_u32_e32 v10, vcc, s75, v10
	s_lshl_b64 s[4:5], s[12:13], 12
	s_nop 0
	v_addc_co_u32_e32 v11, vcc, 0, v11, vcc
	ds_read_b128 v[2:5], v198 offset:4352
	s_waitcnt lgkmcnt(1)
	global_store_dwordx4 v[10:11], v[6:9], off
	s_load_dwordx2 s[12:13], s[0:1], 0xc8
	s_waitcnt lgkmcnt(0)
	s_add_u32 s4, s12, s4
	s_addc_u32 s5, s13, s5
	v_lshl_add_u64 v[10:11], s[4:5], 0, v[0:1]
	s_or_b32 s12, s2, 5
	v_lshl_add_u64 v[10:11], v[10:11], 0, v[168:169]
	s_ashr_i32 s13, s12, 31
	v_add_co_u32_e32 v10, vcc, s75, v10
	s_lshl_b64 s[4:5], s[12:13], 12
	s_nop 0
	v_addc_co_u32_e32 v11, vcc, 0, v11, vcc
	ds_read_b128 v[6:9], v198 offset:5440
	s_waitcnt lgkmcnt(1)
	global_store_dwordx4 v[10:11], v[2:5], off
	s_load_dwordx2 s[12:13], s[0:1], 0xc8
	s_waitcnt lgkmcnt(0)
	s_add_u32 s4, s12, s4
	s_addc_u32 s5, s13, s5
	v_lshl_add_u64 v[10:11], s[4:5], 0, v[0:1]
	s_or_b32 s12, s2, 6
	v_lshl_add_u64 v[10:11], v[10:11], 0, v[168:169]
	s_ashr_i32 s13, s12, 31
	v_add_co_u32_e32 v10, vcc, s75, v10
	s_lshl_b64 s[4:5], s[12:13], 12
	s_nop 0
	v_addc_co_u32_e32 v11, vcc, 0, v11, vcc
	ds_read_b128 v[2:5], v198 offset:6528
	s_waitcnt lgkmcnt(1)
	global_store_dwordx4 v[10:11], v[6:9], off
	s_load_dwordx2 s[12:13], s[0:1], 0xc8
	s_waitcnt lgkmcnt(0)
	s_add_u32 s4, s12, s4
	s_addc_u32 s5, s13, s5
	v_lshl_add_u64 v[10:11], s[4:5], 0, v[0:1]
	s_or_b32 s2, s2, 7
	v_lshl_add_u64 v[10:11], v[10:11], 0, v[168:169]
	s_ashr_i32 s3, s2, 31
	v_add_co_u32_e32 v10, vcc, s75, v10
	s_lshl_b64 s[2:3], s[2:3], 12
	s_nop 0
	v_addc_co_u32_e32 v11, vcc, 0, v11, vcc
	ds_read_b128 v[6:9], v198 offset:7616
	s_waitcnt lgkmcnt(1)
	global_store_dwordx4 v[10:11], v[2:5], off
	s_load_dwordx2 s[4:5], s[0:1], 0xc8
	s_waitcnt lgkmcnt(0)
	s_add_u32 s2, s4, s2
	s_addc_u32 s3, s5, s3
	v_lshl_add_u64 v[2:3], s[2:3], 0, v[0:1]
	v_lshl_add_u64 v[2:3], v[2:3], 0, v[168:169]
	v_add_co_u32_e32 v2, vcc, 0x3ab00000, v2
	s_add_i32 s78, s78, 1
	s_nop 0
	v_addc_co_u32_e32 v3, vcc, 0, v3, vcc
	s_waitcnt lgkmcnt(0)
	global_store_dwordx4 v[2:3], v[6:9], off
	s_waitcnt lgkmcnt(0)
	s_cmp_eq_u32 s78, s68
	s_cselect_b64 s[12:13], -1, 0
	s_barrier

; DI unsigned short f2bf1(float f) { return (unsigned short)(cvtpk(f, 0.f) & 0xffffu); }
; #define LDS_WAIT() asm volatile("s_waitcnt lgkmcnt(0)" ::: "memory")
; DI int crow(int r, int hi) { return (r & 3) + 8 * (r >> 2) + 4 * hi; }
; DI void nsa_stage_out(att::Core<128>& c, bf16_t* stg, float* ws, float fac, bool first, int r32, int hi) {
;     if (hi == 0) ws[r32] = fac;
;     LDS_WAIT();
; #pragma unroll
;     for (int r = 0; r < 16; ++r) { const int orow = att::crow(r, hi); const float f = ws[orow];
; #pragma unroll
;         for (int d0 = 0; d0 < 4; ++d0) { bf16_t* p = stg + orow * 136 + d0 * 32 + r32; float v = c.o[d0][r] * f; if (!first) v += bf2f(*p); *p = f2bf1(v); } }
;     LDS_WAIT();
; }
.LBB0_879:
	s_or_b64 exec, exec, s[2:3]
	s_waitcnt lgkmcnt(0)
	ds_read_b32 v86, v182
	ds_read_b32 v87, v182 offset:4
	ds_read_u16 v203, v199
	ds_read_u16 v204, v199 offset:64
	ds_read_u16 v205, v199 offset:128
	ds_read_u16 v206, v199 offset:192
	ds_read_u16 v207, v200
	ds_read_u16 v208, v200 offset:64
	ds_read_u16 v209, v200 offset:128
	ds_read_u16 v210, v200 offset:192
	s_waitcnt lgkmcnt(0)
	v_lshlrev_b32_e32 v203, 16, v203
	v_lshlrev_b32_e32 v204, 16, v204
	v_lshlrev_b32_e32 v205, 16, v205
	v_lshlrev_b32_e32 v206, 16, v206
	v_lshlrev_b32_e32 v207, 16, v207
	v_lshlrev_b32_e32 v208, 16, v208
	v_lshlrev_b32_e32 v209, 16, v209
	v_lshlrev_b32_e32 v210, 16, v210
	v_fmac_f32_e32 v203, v50, v86
	v_fmac_f32_e32 v204, v34, v86
	v_fmac_f32_e32 v205, v18, v86
	v_fmac_f32_e32 v206, v2, v86
	v_fmac_f32_e32 v207, v51, v87
	v_fmac_f32_e32 v208, v35, v87
	v_fmac_f32_e32 v209, v19, v87
	v_fmac_f32_e32 v210, v3, v87
	v_cvt_pk_bf16_f32 v203, v203, v1
	v_cvt_pk_bf16_f32 v204, v204, v1
	v_cvt_pk_bf16_f32 v205, v205, v1
	v_cvt_pk_bf16_f32 v206, v206, v1
	v_cvt_pk_bf16_f32 v207, v207, v1
	v_cvt_pk_bf16_f32 v208, v208, v1
	v_cvt_pk_bf16_f32 v209, v209, v1
	v_cvt_pk_bf16_f32 v210, v210, v1
	ds_write_b16 v199, v203
	ds_write_b16 v199, v204 offset:64
	ds_write_b16 v199, v205 offset:128
	ds_write_b16 v199, v206 offset:192
	ds_write_b16 v200, v207
	ds_write_b16 v200, v208 offset:64
	ds_write_b16 v200, v209 offset:128
	ds_write_b16 v200, v210 offset:192
	s_waitcnt lgkmcnt(5)
	ds_read_b32 v86, v182 offset:8
	ds_read_b32 v87, v182 offset:12
	ds_read_u16 v203, v200 offset:272
	ds_read_u16 v204, v200 offset:336
	ds_read_u16 v205, v200 offset:400
	ds_read_u16 v206, v200 offset:464
	ds_read_u16 v207, v200 offset:544
	ds_read_u16 v208, v200 offset:608
	ds_read_u16 v209, v200 offset:672
	ds_read_u16 v210, v200 offset:736
	s_waitcnt lgkmcnt(0)
	v_lshlrev_b32_e32 v203, 16, v203
	v_lshlrev_b32_e32 v204, 16, v204
	v_lshlrev_b32_e32 v205, 16, v205
	v_lshlrev_b32_e32 v206, 16, v206
	v_lshlrev_b32_e32 v207, 16, v207
	v_lshlrev_b32_e32 v208, 16, v208
	v_lshlrev_b32_e32 v209, 16, v209
	v_lshlrev_b32_e32 v210, 16, v210
	v_fmac_f32_e32 v203, v52, v86
	v_fmac_f32_e32 v204, v36, v86
	v_fmac_f32_e32 v205, v20, v86
	v_fmac_f32_e32 v206, v4, v86
	v_fmac_f32_e32 v207, v53, v87
	v_fmac_f32_e32 v208, v37, v87
	v_fmac_f32_e32 v209, v21, v87
	v_fmac_f32_e32 v210, v5, v87
	v_cvt_pk_bf16_f32 v203, v203, v1
	v_cvt_pk_bf16_f32 v204, v204, v1
	v_cvt_pk_bf16_f32 v205, v205, v1
	v_cvt_pk_bf16_f32 v206, v206, v1
	v_cvt_pk_bf16_f32 v207, v207, v1
	v_cvt_pk_bf16_f32 v208, v208, v1
	v_cvt_pk_bf16_f32 v209, v209, v1
	v_cvt_pk_bf16_f32 v210, v210, v1
	ds_write_b16 v200, v203 offset:272
	ds_write_b16 v200, v204 offset:336
	ds_write_b16 v200, v205 offset:400
	ds_write_b16 v200, v206 offset:464
	ds_write_b16 v200, v207 offset:544
	ds_write_b16 v200, v208 offset:608
	ds_write_b16 v200, v209 offset:672
	ds_write_b16 v200, v210 offset:736
	s_waitcnt lgkmcnt(5)
	ds_read_b32 v86, v182 offset:32
	ds_read_b32 v87, v182 offset:36
	ds_read_u16 v203, v200 offset:1904
	ds_read_u16 v204, v200 offset:1968
	ds_read_u16 v205, v200 offset:2032
	ds_read_u16 v206, v200 offset:2096
	ds_read_u16 v207, v200 offset:2176
	ds_read_u16 v208, v200 offset:2240
	ds_read_u16 v209, v200 offset:2304
	ds_read_u16 v210, v200 offset:2368
	s_waitcnt lgkmcnt(0)
	v_lshlrev_b32_e32 v203, 16, v203
	v_lshlrev_b32_e32 v204, 16, v204
	v_lshlrev_b32_e32 v205, 16, v205
	v_lshlrev_b32_e32 v206, 16, v206
	v_lshlrev_b32_e32 v207, 16, v207
	v_lshlrev_b32_e32 v208, 16, v208
	v_lshlrev_b32_e32 v209, 16, v209
	v_lshlrev_b32_e32 v210, 16, v210
	v_fmac_f32_e32 v203, v54, v86
	v_fmac_f32_e32 v204, v38, v86
	v_fmac_f32_e32 v205, v22, v86
	v_fmac_f32_e32 v206, v6, v86
	v_fmac_f32_e32 v207, v55, v87
	v_fmac_f32_e32 v208, v39, v87
	v_fmac_f32_e32 v209, v23, v87
	v_fmac_f32_e32 v210, v7, v87
	v_cvt_pk_bf16_f32 v203, v203, v1
	v_cvt_pk_bf16_f32 v204, v204, v1
	v_cvt_pk_bf16_f32 v205, v205, v1
	v_cvt_pk_bf16_f32 v206, v206, v1
	v_cvt_pk_bf16_f32 v207, v207, v1
	v_cvt_pk_bf16_f32 v208, v208, v1
	v_cvt_pk_bf16_f32 v209, v209, v1
	v_cvt_pk_bf16_f32 v210, v210, v1
	ds_write_b16 v200, v203 offset:1904
	ds_write_b16 v200, v204 offset:1968
	ds_write_b16 v200, v205 offset:2032
	ds_write_b16 v200, v206 offset:2096
	ds_write_b16 v200, v207 offset:2176
	ds_write_b16 v200, v208 offset:2240
	ds_write_b16 v200, v209 offset:2304
	ds_write_b16 v200, v210 offset:2368
	s_waitcnt lgkmcnt(5)
	ds_read_b32 v86, v182 offset:40
	ds_read_b32 v87, v182 offset:44
	ds_read_u16 v203, v200 offset:2448
	ds_read_u16 v204, v201 offset:64
	ds_read_u16 v205, v201 offset:128
	ds_read_u16 v206, v201 offset:192
	ds_read_u16 v207, v201 offset:272
	ds_read_u16 v208, v201 offset:336
	ds_read_u16 v209, v201 offset:400
	ds_read_u16 v210, v201 offset:464
	s_waitcnt lgkmcnt(0)
	v_lshlrev_b32_e32 v203, 16, v203
	v_lshlrev_b32_e32 v204, 16, v204
	v_lshlrev_b32_e32 v205, 16, v205
	v_lshlrev_b32_e32 v206, 16, v206
	v_lshlrev_b32_e32 v207, 16, v207
	v_lshlrev_b32_e32 v208, 16, v208
	v_lshlrev_b32_e32 v209, 16, v209
	v_lshlrev_b32_e32 v210, 16, v210
	v_fmac_f32_e32 v203, v56, v86
	v_fmac_f32_e32 v204, v40, v86
	v_fmac_f32_e32 v205, v24, v86
	v_fmac_f32_e32 v206, v8, v86
	v_fmac_f32_e32 v207, v57, v87
	v_fmac_f32_e32 v208, v41, v87
	v_fmac_f32_e32 v209, v25, v87
	v_fmac_f32_e32 v210, v9, v87
	v_cvt_pk_bf16_f32 v203, v203, v1
	v_cvt_pk_bf16_f32 v204, v204, v1
	v_cvt_pk_bf16_f32 v205, v205, v1
	v_cvt_pk_bf16_f32 v206, v206, v1
	v_cvt_pk_bf16_f32 v207, v207, v1
	v_cvt_pk_bf16_f32 v208, v208, v1
	v_cvt_pk_bf16_f32 v209, v209, v1
	v_cvt_pk_bf16_f32 v210, v210, v1
	ds_write_b16 v200, v203 offset:2448
	ds_write_b16 v201, v204 offset:64
	ds_write_b16 v201, v205 offset:128
	ds_write_b16 v201, v206 offset:192
	ds_write_b16 v201, v207 offset:272
	ds_write_b16 v201, v208 offset:336
	ds_write_b16 v201, v209 offset:400
	ds_write_b16 v201, v210 offset:464
	s_waitcnt lgkmcnt(5)
; DI unsigned short f2bf1(float f) { return (unsigned short)(cvtpk(f, 0.f) & 0xffffu); }
; #define LDS_WAIT() asm volatile("s_waitcnt lgkmcnt(0)" ::: "memory")
; DI int crow(int r, int hi) { return (r & 3) + 8 * (r >> 2) + 4 * hi; }
; DI void nsa_stage_out(att::Core<128>& c, bf16_t* stg, float* ws, float fac, bool first, int r32, int hi) {
;     if (hi == 0) ws[r32] = fac;
;     LDS_WAIT();
; #pragma unroll
;     for (int r = 0; r < 16; ++r) { const int orow = att::crow(r, hi); const float f = ws[orow];
; #pragma unroll
;         for (int d0 = 0; d0 < 4; ++d0) { bf16_t* p = stg + orow * 136 + d0 * 32 + r32; float v = c.o[d0][r] * f; if (!first) v += bf2f(*p); *p = f2bf1(v); } }
;     LDS_WAIT();
; }
	ds_read_b32 v86, v182 offset:64
	ds_read_b32 v87, v182 offset:68
	ds_read_u16 v203, v201 offset:1632
	ds_read_u16 v204, v201 offset:1696
	ds_read_u16 v205, v201 offset:1760
	ds_read_u16 v206, v201 offset:1824
	ds_read_u16 v207, v201 offset:1904
	ds_read_u16 v208, v201 offset:1968
	ds_read_u16 v209, v201 offset:2032
	ds_read_u16 v210, v201 offset:2096
	s_waitcnt lgkmcnt(0)
	v_lshlrev_b32_e32 v203, 16, v203
	v_lshlrev_b32_e32 v204, 16, v204
	v_lshlrev_b32_e32 v205, 16, v205
	v_lshlrev_b32_e32 v206, 16, v206
	v_lshlrev_b32_e32 v207, 16, v207
	v_lshlrev_b32_e32 v208, 16, v208
	v_lshlrev_b32_e32 v209, 16, v209
	v_lshlrev_b32_e32 v210, 16, v210
	v_fmac_f32_e32 v203, v58, v86
	v_fmac_f32_e32 v204, v42, v86
	v_fmac_f32_e32 v205, v26, v86
	v_fmac_f32_e32 v206, v10, v86
	v_fmac_f32_e32 v207, v59, v87
	v_fmac_f32_e32 v208, v43, v87
	v_fmac_f32_e32 v209, v27, v87
	v_fmac_f32_e32 v210, v11, v87
	v_cvt_pk_bf16_f32 v203, v203, v1
	v_cvt_pk_bf16_f32 v204, v204, v1
	v_cvt_pk_bf16_f32 v205, v205, v1
	v_cvt_pk_bf16_f32 v206, v206, v1
	v_cvt_pk_bf16_f32 v207, v207, v1
	v_cvt_pk_bf16_f32 v208, v208, v1
	v_cvt_pk_bf16_f32 v209, v209, v1
	v_cvt_pk_bf16_f32 v210, v210, v1
	ds_write_b16 v201, v203 offset:1632
	ds_write_b16 v201, v204 offset:1696
	ds_write_b16 v201, v205 offset:1760
	ds_write_b16 v201, v206 offset:1824
	ds_write_b16 v201, v207 offset:1904
	ds_write_b16 v201, v208 offset:1968
	ds_write_b16 v201, v209 offset:2032
	ds_write_b16 v201, v210 offset:2096
	s_waitcnt lgkmcnt(5)
	ds_read_b32 v86, v182 offset:72
	ds_read_b32 v87, v182 offset:76
	ds_read_u16 v203, v201 offset:2176
	ds_read_u16 v204, v201 offset:2240
	ds_read_u16 v205, v201 offset:2304
	ds_read_u16 v206, v201 offset:2368
	ds_read_u16 v207, v201 offset:2448
	ds_read_u16 v208, v202 offset:64
	ds_read_u16 v209, v202 offset:128
	ds_read_u16 v210, v202 offset:192
	s_waitcnt lgkmcnt(0)
	v_lshlrev_b32_e32 v203, 16, v203
	v_lshlrev_b32_e32 v204, 16, v204
	v_lshlrev_b32_e32 v205, 16, v205
	v_lshlrev_b32_e32 v206, 16, v206
	v_lshlrev_b32_e32 v207, 16, v207
	v_lshlrev_b32_e32 v208, 16, v208
	v_lshlrev_b32_e32 v209, 16, v209
	v_lshlrev_b32_e32 v210, 16, v210
	v_fmac_f32_e32 v203, v60, v86
	v_fmac_f32_e32 v204, v44, v86
	v_fmac_f32_e32 v205, v28, v86
	v_fmac_f32_e32 v206, v12, v86
	v_fmac_f32_e32 v207, v61, v87
	v_fmac_f32_e32 v208, v45, v87
	v_fmac_f32_e32 v209, v29, v87
	v_fmac_f32_e32 v210, v13, v87
	v_cvt_pk_bf16_f32 v203, v203, v1
	v_cvt_pk_bf16_f32 v204, v204, v1
	v_cvt_pk_bf16_f32 v205, v205, v1
	v_cvt_pk_bf16_f32 v206, v206, v1
	v_cvt_pk_bf16_f32 v207, v207, v1
	v_cvt_pk_bf16_f32 v208, v208, v1
	v_cvt_pk_bf16_f32 v209, v209, v1
	v_cvt_pk_bf16_f32 v210, v210, v1
	ds_write_b16 v201, v203 offset:2176
	ds_write_b16 v201, v204 offset:2240
	ds_write_b16 v201, v205 offset:2304
	ds_write_b16 v201, v206 offset:2368
	ds_write_b16 v201, v207 offset:2448
	ds_write_b16 v202, v208 offset:64
	ds_write_b16 v202, v209 offset:128
	ds_write_b16 v202, v210 offset:192
	s_waitcnt lgkmcnt(5)
	ds_read_b32 v86, v182 offset:96
	ds_read_b32 v87, v182 offset:100
	ds_read_u16 v203, v202 offset:1360
	ds_read_u16 v204, v202 offset:1424
	ds_read_u16 v205, v202 offset:1488
	ds_read_u16 v206, v202 offset:1552
	ds_read_u16 v207, v202 offset:1632
	ds_read_u16 v208, v202 offset:1696
	ds_read_u16 v209, v202 offset:1760
	ds_read_u16 v210, v202 offset:1824
	s_waitcnt lgkmcnt(0)
	v_lshlrev_b32_e32 v203, 16, v203
	v_lshlrev_b32_e32 v204, 16, v204
	v_lshlrev_b32_e32 v205, 16, v205
	v_lshlrev_b32_e32 v206, 16, v206
	v_lshlrev_b32_e32 v207, 16, v207
	v_lshlrev_b32_e32 v208, 16, v208
	v_lshlrev_b32_e32 v209, 16, v209
	v_lshlrev_b32_e32 v210, 16, v210
	v_fmac_f32_e32 v203, v62, v86
	v_fmac_f32_e32 v204, v46, v86
	v_fmac_f32_e32 v205, v30, v86
	v_fmac_f32_e32 v206, v14, v86
	v_fmac_f32_e32 v207, v63, v87
	v_fmac_f32_e32 v208, v47, v87
	v_fmac_f32_e32 v209, v31, v87
	v_fmac_f32_e32 v210, v15, v87
	v_cvt_pk_bf16_f32 v203, v203, v1
	v_cvt_pk_bf16_f32 v204, v204, v1
	v_cvt_pk_bf16_f32 v205, v205, v1
	v_cvt_pk_bf16_f32 v206, v206, v1
	v_cvt_pk_bf16_f32 v207, v207, v1
	v_cvt_pk_bf16_f32 v208, v208, v1
	v_cvt_pk_bf16_f32 v209, v209, v1
	v_cvt_pk_bf16_f32 v210, v210, v1
	ds_write_b16 v202, v203 offset:1360
	ds_write_b16 v202, v204 offset:1424
	ds_write_b16 v202, v205 offset:1488
	ds_write_b16 v202, v206 offset:1552
	ds_write_b16 v202, v207 offset:1632
	ds_write_b16 v202, v208 offset:1696
	ds_write_b16 v202, v209 offset:1760
	ds_write_b16 v202, v210 offset:1824
	s_waitcnt lgkmcnt(5)
	ds_read_b32 v86, v182 offset:104
	ds_read_b32 v87, v182 offset:108
	ds_read_u16 v203, v202 offset:1904
	ds_read_u16 v204, v202 offset:1968
	ds_read_u16 v205, v202 offset:2032
	ds_read_u16 v206, v202 offset:2096
	ds_read_u16 v207, v202 offset:2176
	ds_read_u16 v208, v202 offset:2240
	ds_read_u16 v209, v202 offset:2304
	ds_read_u16 v210, v202 offset:2368
	s_waitcnt lgkmcnt(0)
; DI unsigned short f2bf1(float f) { return (unsigned short)(cvtpk(f, 0.f) & 0xffffu); }
; #define LDS_WAIT() asm volatile("s_waitcnt lgkmcnt(0)" ::: "memory")
; DI int crow(int r, int hi) { return (r & 3) + 8 * (r >> 2) + 4 * hi; }
; DI void nsa_stage_out(att::Core<128>& c, bf16_t* stg, float* ws, float fac, bool first, int r32, int hi) {
;     if (hi == 0) ws[r32] = fac;
;     LDS_WAIT();
; #pragma unroll
;     for (int r = 0; r < 16; ++r) { const int orow = att::crow(r, hi); const float f = ws[orow];
; #pragma unroll
;         for (int d0 = 0; d0 < 4; ++d0) { bf16_t* p = stg + orow * 136 + d0 * 32 + r32; float v = c.o[d0][r] * f; if (!first) v += bf2f(*p); *p = f2bf1(v); } }
;     LDS_WAIT();
; }
; DI void nsa_attention(int L2, char* lds, int vcu, int G, int tid, int wave, int lane) {
;     ...
;         {
;             att::core_reset<128>(c, att::M_INIT, 0.f);
;             SeqRange seq; seq.lo = qt - 8 < 0 ? 0 : qt - 8; seq.hi = qt;
;             MaskWin mk; mk.t = t; mk.w = 512; mk.tmin = t0; mk.tmax = t0 + 63;
	v_lshlrev_b32_e32 v203, 16, v203
	v_lshlrev_b32_e32 v204, 16, v204
	v_lshlrev_b32_e32 v205, 16, v205
	v_lshlrev_b32_e32 v206, 16, v206
	v_lshlrev_b32_e32 v207, 16, v207
	v_lshlrev_b32_e32 v208, 16, v208
	v_lshlrev_b32_e32 v209, 16, v209
	v_lshlrev_b32_e32 v210, 16, v210
	v_fmac_f32_e32 v203, v64, v86
	v_fmac_f32_e32 v204, v48, v86
	v_fmac_f32_e32 v205, v32, v86
	v_fmac_f32_e32 v206, v16, v86
	v_fmac_f32_e32 v207, v65, v87
	v_fmac_f32_e32 v208, v49, v87
	v_fmac_f32_e32 v209, v33, v87
	v_fmac_f32_e32 v210, v17, v87
	v_cvt_pk_bf16_f32 v203, v203, v1
	v_cvt_pk_bf16_f32 v204, v204, v1
	v_cvt_pk_bf16_f32 v205, v205, v1
	v_cvt_pk_bf16_f32 v206, v206, v1
	v_cvt_pk_bf16_f32 v207, v207, v1
	v_cvt_pk_bf16_f32 v208, v208, v1
	v_cvt_pk_bf16_f32 v209, v209, v1
	v_cvt_pk_bf16_f32 v210, v210, v1
	ds_write_b16 v202, v203 offset:1904
	ds_write_b16 v202, v204 offset:1968
	ds_write_b16 v202, v205 offset:2032
	ds_write_b16 v202, v206 offset:2096
	ds_write_b16 v202, v207 offset:2176
	ds_write_b16 v202, v208 offset:2240
	ds_write_b16 v202, v209 offset:2304
	ds_write_b16 v202, v210 offset:2368
	s_max_i32 s2, s91, 8
	s_add_i32 s92, s2, -8
	v_mov_b32_e32 v67, v165
	s_cmp_gt_i32 s92, s91
	v_mov_b32_e32 v66, v167
	v_mov_b32_e32 v68, 0
	v_mov_b32_e32 v50, 0
	v_mov_b32_e32 v34, 0
	v_mov_b32_e32 v18, 0
	v_mov_b32_e32 v51, 0
	v_mov_b32_e32 v35, 0
	v_mov_b32_e32 v19, 0
	v_mov_b32_e32 v3, 0
	v_mov_b32_e32 v52, 0
	v_mov_b32_e32 v36, 0
	v_mov_b32_e32 v20, 0
	v_mov_b32_e32 v4, 0
	v_mov_b32_e32 v53, 0
	v_mov_b32_e32 v37, 0
	v_mov_b32_e32 v21, 0
	v_mov_b32_e32 v5, 0
	v_mov_b32_e32 v54, 0
	v_mov_b32_e32 v38, 0
	v_mov_b32_e32 v22, 0
	v_mov_b32_e32 v6, 0
	v_mov_b32_e32 v55, 0
	v_mov_b32_e32 v39, 0
	v_mov_b32_e32 v23, 0
	v_mov_b32_e32 v7, 0
	v_mov_b32_e32 v56, 0
	v_mov_b32_e32 v40, 0
	v_mov_b32_e32 v24, 0
	v_mov_b32_e32 v8, 0
	v_mov_b32_e32 v57, 0
	v_mov_b32_e32 v41, 0
	v_mov_b32_e32 v25, 0
	v_mov_b32_e32 v9, 0
	v_mov_b32_e32 v58, 0
	v_mov_b32_e32 v42, 0
	v_mov_b32_e32 v26, 0
	v_mov_b32_e32 v10, 0
	v_mov_b32_e32 v59, 0
	v_mov_b32_e32 v43, 0
	v_mov_b32_e32 v27, 0
	v_mov_b32_e32 v11, 0
	v_mov_b32_e32 v60, 0
	v_mov_b32_e32 v44, 0
	v_mov_b32_e32 v28, 0
	v_mov_b32_e32 v12, 0
	v_mov_b32_e32 v61, 0
	v_mov_b32_e32 v45, 0
	v_mov_b32_e32 v29, 0
	v_mov_b32_e32 v13, 0
	v_mov_b32_e32 v62, 0
	v_mov_b32_e32 v46, 0
	v_mov_b32_e32 v30, 0
	v_mov_b32_e32 v14, 0
	v_mov_b32_e32 v63, 0
	v_mov_b32_e32 v47, 0
	v_mov_b32_e32 v31, 0
	v_mov_b32_e32 v15, 0
	v_mov_b32_e32 v64, 0
	v_mov_b32_e32 v48, 0
	v_mov_b32_e32 v32, 0
	v_mov_b32_e32 v16, 0
	v_mov_b32_e32 v65, 0
	v_mov_b32_e32 v49, 0
	v_mov_b32_e32 v33, 0
	s_waitcnt lgkmcnt(0)
	v_mov_b32_e32 v17, 0
	v_mov_b32_e32 v2, 0
	s_load_dwordx2 s[12:13], s[0:1], 0xc8
	s_waitcnt lgkmcnt(0)
	s_load_dwordx2 s[2:3], s[0:1], 0xc8
	s_waitcnt lgkmcnt(0)
	s_cbranch_scc1 .LBB0_898
; DI int v_rd_base(int lane) { return ((lane & 3) << 3) | (((lane >> 2) & 3) << 6) | (((lane >> 4) & 1) << 5) | (((lane >> 5) & 1) << 8); }
; #define LBAR() asm volatile("s_waitcnt lgkmcnt(0)\n\ts_barrier" ::: "memory")
; template <int D, bool PIPE, class Seq, class MaskF, class KX>
; DI void run_tiles(Core<D>& c, char* kv, float* ws, const bf16_t* Kg0, const bf16_t* Vg0, int pitch, const Seq& seq, const MaskF& mk, const KX& kx, int tid_, int lane_) {
;     ...
;     int t0; if (!seq.first(t0)) return;
;     const int vb0 = (int)(uintptr_t)(kv + 2 * KB) + v_rd_base(lane);
;     StgH<D> sk, sv;
;     if constexpr (!PIPE) {
;         stg_ld<D>(sk, Kg0 + (size_t)64 * t0 * pitch, pitch, tid); stg_ld<D>(sv, Vg0 + (size_t)64 * t0 * pitch, pitch, tid);
;         LBAR();
;         kx.apply(sk, t0, tid); stg_wrK<D>(sk, kv, tid); stg_wrV<D>(sv, kv + 2 * KB, tid);
;         LBAR();
; DI void nsa_attention(int L2, char* lds, int vcu, int G, int tid, int wave, int lane) {
;     ...
;         {
;             att::core_reset<128>(c, att::M_INIT, 0.f);
;             SeqRange seq; seq.lo = qt - 8 < 0 ? 0 : qt - 8; seq.hi = qt;
;             MaskWin mk; mk.t = t; mk.w = 512; mk.tmin = t0; mk.tmax = t0 + 63;
;             att::run_tiles<128, false>(c, lds + NSL_KV, ws, NSA_QKV + (size_t)b * T * NS_N + NS_KW + g * 128, NSA_QKV + (size_t)b * T * NS_N + NS_VW + g * 128, NS_N, seq, mk, KxNone(), tid, lane);
	s_lshl_b64 s[14:15], s[48:49], 1
	s_add_u32 s4, s12, s14
	s_addc_u32 s5, s13, s15
	s_lshl_b32 s10, s56, 1
	s_add_u32 s4, s4, s10
	s_addc_u32 s5, s5, 0
	s_add_u32 s94, s4, 0x2fb02000
	s_addc_u32 s4, s5, 0
	s_add_u32 s2, s2, s14
	s_addc_u32 s3, s3, s15
	s_add_u32 s2, s2, s10
	s_addc_u32 s3, s3, 0
	s_add_u32 s5, s2, 0x2fb02400
	v_ashrrev_i32_e32 v3, 4, v67
	s_addc_u32 s85, s3, 0
	s_mul_i32 s14, s92, 0xa0000
	s_movk_i32 s15, 0x1400
	v_add_u32_e32 v9, 32, v3
	s_mul_hi_u32 s10, s92, 0xa0000
	s_add_u32 s2, s94, s14
	v_lshlrev_b32_e32 v8, 3, v67
	v_mad_i64_i32 v[4:5], s[12:13], v3, s15, 0
	v_mad_i64_i32 v[6:7], s[12:13], v9, s15, 0
	s_addc_u32 s3, s4, s10
	v_and_b32_e32 v2, 0x78, v8
	v_lshlrev_b64 v[170:171], 1, v[4:5]
	v_lshlrev_b64 v[172:173], 1, v[6:7]
	v_lshl_add_u64 v[4:5], s[2:3], 0, v[170:171]
	v_lshlrev_b32_e32 v0, 1, v2
	v_lshl_add_u64 v[6:7], s[2:3], 0, v[172:173]
	s_add_u32 s2, s5, s14
	v_lshl_add_u64 v[4:5], v[4:5], 0, v[0:1]
	s_addc_u32 s3, s85, s10
	v_lshl_add_u64 v[6:7], v[6:7], 0, v[0:1]
	global_load_dwordx4 v[98:101], v[4:5], off
	global_load_dwordx4 v[102:105], v[6:7], off
	v_lshl_add_u64 v[4:5], s[2:3], 0, v[170:171]
	v_lshl_add_u64 v[4:5], v[4:5], 0, v[0:1]
	v_lshl_add_u64 v[6:7], s[2:3], 0, v[172:173]
	v_lshl_add_u64 v[6:7], v[6:7], 0, v[0:1]
	global_load_dwordx4 v[106:109], v[4:5], off
	global_load_dwordx4 v[144:147], v[6:7], off
	v_ashrrev_i32_e32 v0, 5, v66
	v_and_b32_e32 v4, 31, v66
	v_lshlrev_b32_e32 v6, 4, v66
	v_and_b32_e32 v13, 0xfffff0, v3
	v_lshlrev_b32_e32 v14, 1, v3
	v_and_b32_e32 v12, 0xc0, v6
	v_lshlrev_b32_e32 v175, 8, v4
	v_and_b32_e32 v176, 0x70, v6
	v_lshlrev_b32_e32 v177, 4, v0
	v_lshlrev_b32_e32 v203, 2, v0
	v_lshl_add_u32 v204, v4, 2, s11
	v_and_or_b32 v0, v14, 8, v13
	v_and_b32_e32 v4, 0xfffff0, v9
	v_lshlrev_b32_e32 v6, 1, v9
	v_lshrrev_b32_e32 v15, 1, v3
	v_bfe_u32 v8, v8, 5, 2
	v_and_b32_e32 v3, 3, v3
	v_lshrrev_b32_e32 v0, 1, v0
	v_and_or_b32 v4, v6, 8, v4
	v_lshlrev_b32_e32 v10, 4, v67
	v_and_b32_e32 v11, 0x70, v67
	s_movk_i32 s2, 0xf0
	v_and_or_b32 v3, v15, 4, v3
	v_or_b32_e32 v0, v0, v8
	v_lshrrev_b32_e32 v4, 1, v4
	v_lshlrev_b32_e32 v7, 1, v66
	v_bitop3_b32 v11, v10, v11, s2 bitop3:0x6c
	v_and_b32_e32 v16, 48, v10
	s_movk_i32 s2, 0xff00
	v_lshlrev_b32_e32 v3, 6, v3
	v_lshlrev_b32_e32 v0, 9, v0
	v_or_b32_e32 v4, v4, v8
	v_lshlrev_b32_e32 v5, 3, v66
	v_and_b32_e32 v7, 32, v7
	v_and_or_b32 v205, v10, s2, v11
	s_movk_i32 s2, 0x118
	v_or3_b32 v212, v0, v3, v16
	v_lshlrev_b32_e32 v0, 9, v4
	v_and_or_b32 v5, v5, s2, v7
	v_add_u32_e32 v7, 0, v205
	v_or3_b32 v213, v0, v3, v16
	s_add_i32 s90, s86, 0xfffffe3f
	s_add_i32 s2, 0, 0x8000
	v_add_u32_e32 v4, 0, v212
	v_add_u32_e32 v0, 0, v213
	s_waitcnt lgkmcnt(0)
	s_barrier
	s_cmp_lg_u32 s2, -1
	v_writelane_b32 v255, s80, 22
	s_cselect_b32 s2, s2, 0
	v_mov_b32_e32 v50, v1
	v_mov_b32_e32 v51, v1
	v_writelane_b32 v255, s79, 25
	v_add3_u32 v214, v12, s2, v5
	v_mov_b32_e32 v52, v1
	v_mov_b32_e32 v53, v1
	v_mov_b32_e32 v54, v1
	v_mov_b32_e32 v55, v1
	s_waitcnt vmcnt(3)
	ds_write_b128 v7, v[98:101]
	s_waitcnt vmcnt(2)
	ds_write_b128 v7, v[102:105] offset:8192
	s_waitcnt vmcnt(1)
	ds_write_b128 v4, v[106:109] offset:32768
	s_waitcnt vmcnt(0)
	ds_write_b128 v0, v[144:147] offset:32768
	s_waitcnt lgkmcnt(0)
	s_barrier
	v_mov_b32_e32 v56, v1
	v_mov_b32_e32 v57, v1
	v_mov_b32_e32 v58, v1
	v_mov_b32_e32 v59, v1
	v_mov_b32_e32 v60, v1
	v_mov_b32_e32 v61, v1
	v_mov_b32_e32 v62, v1
	v_mov_b32_e32 v63, v1
	v_mov_b32_e32 v64, v1
	v_mov_b32_e32 v65, v1
	v_lshlrev_b32_e32 v0, 1, v2
	v_mov_b64_e32 v[34:35], v[50:51]
	v_mov_b64_e32 v[18:19], v[50:51]
	v_mov_b64_e32 v[2:3], v[50:51]
	v_writelane_b32 v255, s78, 21
	s_mov_b32 s84, 0x42b504f3
	v_cmp_gt_u32_e64 s[12:13], 32, v66
	v_add_u32_e32 v174, 0xfffffe00, v169
	v_add_u32_e32 v206, 0x60, v177
	v_add_u32_e32 v207, 0x80, v177
	v_add_u32_e32 v208, 0xa0, v177
	v_add_u32_e32 v209, 0xc0, v177
	v_add_u32_e32 v210, 0xe0, v177
	v_add_u32_e32 v211, s11, v177
	s_mov_b32 s10, 0
	v_mov_b32_e32 v216, 0
	v_mov_b32_e32 v215, 0xc6ea6000
	v_mov_b64_e32 v[36:37], v[52:53]
	v_mov_b64_e32 v[38:39], v[54:55]
	v_mov_b64_e32 v[40:41], v[56:57]
	v_mov_b64_e32 v[42:43], v[58:59]
	v_mov_b64_e32 v[44:45], v[60:61]
	v_mov_b64_e32 v[46:47], v[62:63]
	v_mov_b64_e32 v[48:49], v[64:65]
	v_mov_b64_e32 v[20:21], v[52:53]
	v_mov_b64_e32 v[22:23], v[54:55]
	v_mov_b64_e32 v[24:25], v[56:57]
	v_mov_b64_e32 v[26:27], v[58:59]
	v_mov_b64_e32 v[28:29], v[60:61]
	v_mov_b64_e32 v[30:31], v[62:63]
	v_mov_b64_e32 v[32:33], v[64:65]
	v_mov_b64_e32 v[4:5], v[52:53]
	v_mov_b64_e32 v[6:7], v[54:55]
	v_mov_b64_e32 v[8:9], v[56:57]
	v_mov_b64_e32 v[10:11], v[58:59]
	v_mov_b64_e32 v[12:13], v[60:61]
	v_mov_b64_e32 v[14:15], v[62:63]
	v_mov_b64_e32 v[16:17], v[64:65]
